# v28 plus GU and Down steady loops: LDS read addresses precomputed once per unit, stage bases folded into ds_read offsets (5 VALU adds per iteration removed from the load-phase heads)
# speedup vs baseline: 1.0092x; 1.0092x over previous
.LBB0_531:
	v_add_u32_e32 v240, 0x10000, v147
	s_add_u32 s8, s8, 0x80180
	s_addc_u32 s9, s9, 0
	s_add_u32 s26, s6, 0x200
	s_addc_u32 s27, s7, 0
	s_mov_b32 s28, 0
	v_mov_b32_e32 v2, v138
.LBB0_532:
	s_add_u32 s6, s8, 0xfff80080
	s_addc_u32 s7, s9, -1
	s_add_i32 s29, 0, 0x10000
	s_cmp_eq_u32 s28, 28
	s_cselect_b32 s17, s13, s7
	s_cselect_b32 s16, s12, s6
	s_cselect_b32 s7, s15, s27
	s_cselect_b32 s6, s14, s26
	s_add_i32 s53, 0, 0x14000
	ds_read_b128 v[138:141], v240
	ds_read_b128 v[142:145], v240 offset:1024
	ds_read_b128 v[148:151], v240 offset:2048
	ds_read_b128 v[152:155], v240 offset:3072
	ds_read_b128 v[156:159], v240 offset:16384
	ds_read_b128 v[160:163], v240 offset:17408
	ds_read_b128 v[164:167], v240 offset:18432
	ds_read_b128 v[168:171], v240 offset:19456
	s_mov_b32 m0, s66
	ds_read_b128 v[172:175], v146
	ds_read_b128 v[176:179], v146 offset:1024
	ds_read_b128 v[180:183], v146 offset:2048
	ds_read_b128 v[184:187], v146 offset:3072
	ds_read_b128 v[188:191], v146 offset:4096
	ds_read_b128 v[192:195], v146 offset:5120
	ds_read_b128 v[196:199], v146 offset:6144
	ds_read_b128 v[200:203], v146 offset:7168
	global_load_lds_dwordx4 v2, s[8:9]
	s_mov_b32 m0, s67
	v_mov_b32_e32 v133, v3
	global_load_lds_dwordx4 v132, s[8:9]
	s_waitcnt vmcnt(8)
	s_waitcnt lgkmcnt(0)
	s_barrier
	s_setprio 1
	s_waitcnt lgkmcnt(0)
	v_mfma_f32_16x16x32_f16 v[4:7], v[138:141], v[172:175], v[4:7]
	v_mfma_f32_16x16x32_f16 v[4:7], v[142:145], v[176:179], v[4:7]
	v_mfma_f32_16x16x32_f16 v[8:11], v[152:155], v[176:179], v[8:11]
	v_mfma_f32_16x16x32_f16 v[8:11], v[148:151], v[172:175], v[8:11]
	v_mfma_f32_16x16x32_f16 v[16:19], v[148:151], v[180:183], v[16:19]
	v_mfma_f32_16x16x32_f16 v[16:19], v[152:155], v[184:187], v[16:19]
	v_mfma_f32_16x16x32_f16 v[12:15], v[142:145], v[184:187], v[12:15]
	v_mfma_f32_16x16x32_f16 v[12:15], v[138:141], v[180:183], v[12:15]
	v_mfma_f32_16x16x32_f16 v[20:23], v[138:141], v[188:191], v[20:23]
	v_mfma_f32_16x16x32_f16 v[20:23], v[142:145], v[192:195], v[20:23]
	v_mfma_f32_16x16x32_f16 v[24:27], v[152:155], v[192:195], v[24:27]
	v_mfma_f32_16x16x32_f16 v[24:27], v[148:151], v[188:191], v[24:27]
	v_mfma_f32_16x16x32_f16 v[32:35], v[148:151], v[196:199], v[32:35]
	v_mfma_f32_16x16x32_f16 v[32:35], v[152:155], v[200:203], v[32:35]
	v_mfma_f32_16x16x32_f16 v[28:31], v[142:145], v[200:203], v[28:31]
	v_mfma_f32_16x16x32_f16 v[28:31], v[138:141], v[196:199], v[28:31]
	s_setprio 0
	s_setprio 1
	v_mfma_f32_16x16x32_f16 v[36:39], v[156:159], v[172:175], v[36:39]
	v_mfma_f32_16x16x32_f16 v[36:39], v[160:163], v[176:179], v[36:39]
	v_mfma_f32_16x16x32_f16 v[40:43], v[168:171], v[176:179], v[40:43]
	v_mfma_f32_16x16x32_f16 v[40:43], v[164:167], v[172:175], v[40:43]
	v_mfma_f32_16x16x32_f16 v[48:51], v[164:167], v[180:183], v[48:51]
	v_mfma_f32_16x16x32_f16 v[48:51], v[168:171], v[184:187], v[48:51]
	v_mfma_f32_16x16x32_f16 v[44:47], v[160:163], v[184:187], v[44:47]
	v_mfma_f32_16x16x32_f16 v[44:47], v[156:159], v[180:183], v[44:47]
	v_mfma_f32_16x16x32_f16 v[52:55], v[156:159], v[188:191], v[52:55]
	v_mfma_f32_16x16x32_f16 v[52:55], v[160:163], v[192:195], v[52:55]
	v_mfma_f32_16x16x32_f16 v[56:59], v[168:171], v[192:195], v[56:59]
	v_mfma_f32_16x16x32_f16 v[56:59], v[164:167], v[188:191], v[56:59]
	v_mfma_f32_16x16x32_f16 v[64:67], v[164:167], v[196:199], v[64:67]
	v_mfma_f32_16x16x32_f16 v[64:67], v[168:171], v[200:203], v[64:67]
	s_setprio 2
	s_barrier
	v_mfma_f32_16x16x32_f16 v[60:63], v[160:163], v[200:203], v[60:63]
	v_mfma_f32_16x16x32_f16 v[60:63], v[156:159], v[196:199], v[60:63]
	s_setprio 0
	s_add_i32 s29, s29, s38
	s_mov_b32 m0, s29
	ds_read_b128 v[172:175], v146 offset:16384
	ds_read_b128 v[176:179], v146 offset:17408
	ds_read_b128 v[180:183], v146 offset:18432
	ds_read_b128 v[184:187], v146 offset:19456
	ds_read_b128 v[188:191], v146 offset:20480
	ds_read_b128 v[192:195], v146 offset:21504
	ds_read_b128 v[196:199], v146 offset:22528
	ds_read_b128 v[200:203], v146 offset:23552
	global_load_lds_dwordx4 v136, s[6:7]
	s_add_i32 m0, s29, 0x2000
	s_add_u32 s40, s6, 0x80000
	s_addc_u32 s41, s7, 0
	s_add_i32 s29, s53, s38
	global_load_lds_dwordx4 v134, s[6:7]
	s_mov_b32 m0, s29
	v_mov_b32_e32 v137, v3
	global_load_lds_dwordx4 v136, s[40:41]
	s_add_i32 m0, s29, 0x2000
	v_mov_b32_e32 v135, v3
	global_load_lds_dwordx4 v134, s[40:41]
	s_mov_b32 m0, s58
	v_lshl_add_u64 v[204:205], s[6:7], 0, v[136:137]
	global_load_lds_dwordx4 v2, s[16:17]
	s_mov_b32 m0, s59
	v_lshl_add_u64 v[206:207], s[6:7], 0, v[134:135]
	global_load_lds_dwordx4 v132, s[16:17]
	s_waitcnt vmcnt(8)
	s_waitcnt lgkmcnt(0)
	v_lshl_add_u64 v[208:209], s[16:17], 0, v[2:3]
	v_lshl_add_u64 v[210:211], s[16:17], 0, v[132:133]
	s_barrier
	s_setprio 1
	s_waitcnt lgkmcnt(0)
	v_mfma_f32_16x16x32_f16 v[68:71], v[138:141], v[172:175], v[68:71]
	v_mfma_f32_16x16x32_f16 v[68:71], v[142:145], v[176:179], v[68:71]
	v_mfma_f32_16x16x32_f16 v[72:75], v[152:155], v[176:179], v[72:75]
	v_mfma_f32_16x16x32_f16 v[72:75], v[148:151], v[172:175], v[72:75]
	v_mfma_f32_16x16x32_f16 v[80:83], v[148:151], v[180:183], v[80:83]
	v_mfma_f32_16x16x32_f16 v[80:83], v[152:155], v[184:187], v[80:83]
	v_mfma_f32_16x16x32_f16 v[76:79], v[142:145], v[184:187], v[76:79]
	v_mfma_f32_16x16x32_f16 v[76:79], v[138:141], v[180:183], v[76:79]
	v_mfma_f32_16x16x32_f16 v[84:87], v[138:141], v[188:191], v[84:87]
	v_mfma_f32_16x16x32_f16 v[84:87], v[142:145], v[192:195], v[84:87]
	v_mfma_f32_16x16x32_f16 v[88:91], v[152:155], v[192:195], v[88:91]
	v_mfma_f32_16x16x32_f16 v[88:91], v[148:151], v[188:191], v[88:91]
	v_mfma_f32_16x16x32_f16 v[96:99], v[148:151], v[196:199], v[96:99]
	v_mfma_f32_16x16x32_f16 v[96:99], v[152:155], v[200:203], v[96:99]
	v_mfma_f32_16x16x32_f16 v[92:95], v[142:145], v[200:203], v[92:95]
	v_mfma_f32_16x16x32_f16 v[92:95], v[138:141], v[196:199], v[92:95]
	s_setprio 0
	s_setprio 1
	v_mfma_f32_16x16x32_f16 v[100:103], v[156:159], v[172:175], v[100:103]
	v_mfma_f32_16x16x32_f16 v[100:103], v[160:163], v[176:179], v[100:103]
	v_mfma_f32_16x16x32_f16 v[104:107], v[168:171], v[176:179], v[104:107]
	v_mfma_f32_16x16x32_f16 v[104:107], v[164:167], v[172:175], v[104:107]
	v_mfma_f32_16x16x32_f16 v[112:115], v[164:167], v[180:183], v[112:115]
	v_mfma_f32_16x16x32_f16 v[112:115], v[168:171], v[184:187], v[112:115]
	v_mfma_f32_16x16x32_f16 v[108:111], v[160:163], v[184:187], v[108:111]
	v_mfma_f32_16x16x32_f16 v[108:111], v[156:159], v[180:183], v[108:111]
	v_mfma_f32_16x16x32_f16 v[116:119], v[156:159], v[188:191], v[116:119]
	v_mfma_f32_16x16x32_f16 v[116:119], v[160:163], v[192:195], v[116:119]
	v_mfma_f32_16x16x32_f16 v[120:123], v[168:171], v[192:195], v[120:123]
	v_mfma_f32_16x16x32_f16 v[120:123], v[164:167], v[188:191], v[120:123]
	v_mfma_f32_16x16x32_f16 v[128:131], v[164:167], v[196:199], v[128:131]
	v_mfma_f32_16x16x32_f16 v[128:131], v[168:171], v[200:203], v[128:131]
	s_setprio 2
	s_barrier
	v_mfma_f32_16x16x32_f16 v[124:127], v[160:163], v[200:203], v[124:127]
	v_mfma_f32_16x16x32_f16 v[124:127], v[156:159], v[196:199], v[124:127]
	s_setprio 0
	s_add_i32 s29, 0, 0x18000
	s_add_i32 s40, 0, 0x1c000
	ds_read_b128 v[138:141], v240 offset:32768
	ds_read_b128 v[142:145], v240 offset:33792
	ds_read_b128 v[148:151], v240 offset:34816
	ds_read_b128 v[152:155], v240 offset:35840
	ds_read_b128 v[156:159], v240 offset:49152
	ds_read_b128 v[160:163], v240 offset:50176
	ds_read_b128 v[164:167], v240 offset:51200
	ds_read_b128 v[168:171], v240 offset:52224
	s_add_u32 s16, s16, 0x80000
	s_addc_u32 s17, s17, 0
	s_mov_b32 m0, s60
	ds_read_b128 v[172:175], v146 offset:32768
	ds_read_b128 v[176:179], v146 offset:33792
	ds_read_b128 v[180:183], v146 offset:34816
	ds_read_b128 v[184:187], v146 offset:35840
	ds_read_b128 v[188:191], v146 offset:36864
	ds_read_b128 v[192:195], v146 offset:37888
	ds_read_b128 v[196:199], v146 offset:38912
	ds_read_b128 v[200:203], v146 offset:39936
	global_load_lds_dwordx4 v2, s[16:17]
	s_mov_b32 m0, s61
	s_nop 0
	global_load_lds_dwordx4 v132, s[16:17]
	s_waitcnt vmcnt(8)
	s_waitcnt lgkmcnt(0)
	s_barrier
	s_setprio 1
	s_waitcnt lgkmcnt(0)
	v_mfma_f32_16x16x32_f16 v[4:7], v[138:141], v[172:175], v[4:7]
	v_mfma_f32_16x16x32_f16 v[4:7], v[142:145], v[176:179], v[4:7]
	v_mfma_f32_16x16x32_f16 v[8:11], v[152:155], v[176:179], v[8:11]
	v_mfma_f32_16x16x32_f16 v[8:11], v[148:151], v[172:175], v[8:11]
	v_mfma_f32_16x16x32_f16 v[16:19], v[148:151], v[180:183], v[16:19]
	v_mfma_f32_16x16x32_f16 v[16:19], v[152:155], v[184:187], v[16:19]
	v_mfma_f32_16x16x32_f16 v[12:15], v[142:145], v[184:187], v[12:15]
	v_mfma_f32_16x16x32_f16 v[12:15], v[138:141], v[180:183], v[12:15]
	v_mfma_f32_16x16x32_f16 v[20:23], v[138:141], v[188:191], v[20:23]
	v_mfma_f32_16x16x32_f16 v[20:23], v[142:145], v[192:195], v[20:23]
	v_mfma_f32_16x16x32_f16 v[24:27], v[152:155], v[192:195], v[24:27]
	v_mfma_f32_16x16x32_f16 v[24:27], v[148:151], v[188:191], v[24:27]
	v_mfma_f32_16x16x32_f16 v[32:35], v[148:151], v[196:199], v[32:35]
	v_mfma_f32_16x16x32_f16 v[32:35], v[152:155], v[200:203], v[32:35]
	v_mfma_f32_16x16x32_f16 v[28:31], v[142:145], v[200:203], v[28:31]
	v_mfma_f32_16x16x32_f16 v[28:31], v[138:141], v[196:199], v[28:31]
	s_setprio 0
	s_setprio 1
	v_mfma_f32_16x16x32_f16 v[36:39], v[156:159], v[172:175], v[36:39]
	v_mfma_f32_16x16x32_f16 v[36:39], v[160:163], v[176:179], v[36:39]
	v_mfma_f32_16x16x32_f16 v[40:43], v[168:171], v[176:179], v[40:43]
	v_mfma_f32_16x16x32_f16 v[40:43], v[164:167], v[172:175], v[40:43]
	v_mfma_f32_16x16x32_f16 v[48:51], v[164:167], v[180:183], v[48:51]
	v_mfma_f32_16x16x32_f16 v[48:51], v[168:171], v[184:187], v[48:51]
	v_mfma_f32_16x16x32_f16 v[44:47], v[160:163], v[184:187], v[44:47]
	v_mfma_f32_16x16x32_f16 v[44:47], v[156:159], v[180:183], v[44:47]
	v_mfma_f32_16x16x32_f16 v[52:55], v[156:159], v[188:191], v[52:55]
	v_mfma_f32_16x16x32_f16 v[52:55], v[160:163], v[192:195], v[52:55]
	v_mfma_f32_16x16x32_f16 v[56:59], v[168:171], v[192:195], v[56:59]
	v_mfma_f32_16x16x32_f16 v[56:59], v[164:167], v[188:191], v[56:59]
	v_mfma_f32_16x16x32_f16 v[64:67], v[164:167], v[196:199], v[64:67]
	v_mfma_f32_16x16x32_f16 v[64:67], v[168:171], v[200:203], v[64:67]
	s_setprio 2
	s_barrier
	v_mfma_f32_16x16x32_f16 v[60:63], v[160:163], v[200:203], v[60:63]
	v_mfma_f32_16x16x32_f16 v[60:63], v[156:159], v[196:199], v[60:63]
	s_setprio 0
	s_add_i32 s16, s29, s38
	v_lshl_add_u64 v[204:205], v[204:205], 0, s[86:87]
	s_mov_b32 m0, s16
	ds_read_b128 v[172:175], v146 offset:49152
	ds_read_b128 v[176:179], v146 offset:50176
	ds_read_b128 v[180:183], v146 offset:51200
	ds_read_b128 v[184:187], v146 offset:52224
	ds_read_b128 v[188:191], v146 offset:53248
	ds_read_b128 v[192:195], v146 offset:54272
	ds_read_b128 v[196:199], v146 offset:55296
	ds_read_b128 v[200:203], v146 offset:56320
	global_load_lds_dwordx4 v[204:205], off
	s_add_i32 m0, s16, 0x2000
	s_add_u32 s6, s6, 0x80080
	v_lshl_add_u64 v[204:205], v[206:207], 0, s[86:87]
	s_addc_u32 s7, s7, 0
	s_add_i32 s16, s40, s38
	global_load_lds_dwordx4 v[204:205], off
	s_mov_b32 m0, s16
	v_lshl_add_u64 v[204:205], v[208:209], 0, s[86:87]
	global_load_lds_dwordx4 v136, s[6:7]
	s_add_i32 m0, s16, 0x2000
	s_nop 0
	global_load_lds_dwordx4 v134, s[6:7]
	s_mov_b32 m0, s64
	s_nop 0
	global_load_lds_dwordx4 v[204:205], off
	v_lshl_add_u64 v[204:205], v[210:211], 0, s[86:87]
	s_mov_b32 m0, s65
	s_nop 0
	global_load_lds_dwordx4 v[204:205], off
	s_waitcnt vmcnt(8)
	s_waitcnt lgkmcnt(0)
	s_barrier
	s_setprio 1
	s_waitcnt lgkmcnt(0)
	v_mfma_f32_16x16x32_f16 v[68:71], v[138:141], v[172:175], v[68:71]
	v_mfma_f32_16x16x32_f16 v[68:71], v[142:145], v[176:179], v[68:71]
	v_mfma_f32_16x16x32_f16 v[72:75], v[152:155], v[176:179], v[72:75]
	v_mfma_f32_16x16x32_f16 v[72:75], v[148:151], v[172:175], v[72:75]
	v_mfma_f32_16x16x32_f16 v[80:83], v[148:151], v[180:183], v[80:83]
	v_mfma_f32_16x16x32_f16 v[80:83], v[152:155], v[184:187], v[80:83]
	v_mfma_f32_16x16x32_f16 v[76:79], v[142:145], v[184:187], v[76:79]
	v_mfma_f32_16x16x32_f16 v[76:79], v[138:141], v[180:183], v[76:79]
	v_mfma_f32_16x16x32_f16 v[84:87], v[138:141], v[188:191], v[84:87]
	v_mfma_f32_16x16x32_f16 v[84:87], v[142:145], v[192:195], v[84:87]
	v_mfma_f32_16x16x32_f16 v[88:91], v[152:155], v[192:195], v[88:91]
	v_mfma_f32_16x16x32_f16 v[88:91], v[148:151], v[188:191], v[88:91]
	v_mfma_f32_16x16x32_f16 v[96:99], v[148:151], v[196:199], v[96:99]
	v_mfma_f32_16x16x32_f16 v[96:99], v[152:155], v[200:203], v[96:99]
	v_mfma_f32_16x16x32_f16 v[92:95], v[142:145], v[200:203], v[92:95]
	v_mfma_f32_16x16x32_f16 v[92:95], v[138:141], v[196:199], v[92:95]
	s_setprio 0
	s_setprio 1
	v_mfma_f32_16x16x32_f16 v[100:103], v[156:159], v[172:175], v[100:103]
	v_mfma_f32_16x16x32_f16 v[100:103], v[160:163], v[176:179], v[100:103]
	v_mfma_f32_16x16x32_f16 v[104:107], v[168:171], v[176:179], v[104:107]
	v_mfma_f32_16x16x32_f16 v[104:107], v[164:167], v[172:175], v[104:107]
	v_mfma_f32_16x16x32_f16 v[112:115], v[164:167], v[180:183], v[112:115]
	v_mfma_f32_16x16x32_f16 v[112:115], v[168:171], v[184:187], v[112:115]
	v_mfma_f32_16x16x32_f16 v[108:111], v[160:163], v[184:187], v[108:111]
	v_mfma_f32_16x16x32_f16 v[108:111], v[156:159], v[180:183], v[108:111]
	v_mfma_f32_16x16x32_f16 v[116:119], v[156:159], v[188:191], v[116:119]
	v_mfma_f32_16x16x32_f16 v[116:119], v[160:163], v[192:195], v[116:119]
	v_mfma_f32_16x16x32_f16 v[120:123], v[168:171], v[192:195], v[120:123]
	v_mfma_f32_16x16x32_f16 v[120:123], v[164:167], v[188:191], v[120:123]
	v_mfma_f32_16x16x32_f16 v[128:131], v[164:167], v[196:199], v[128:131]
	v_mfma_f32_16x16x32_f16 v[128:131], v[168:171], v[200:203], v[128:131]
	s_setprio 2
	s_barrier
	v_mfma_f32_16x16x32_f16 v[124:127], v[160:163], v[200:203], v[124:127]
	v_mfma_f32_16x16x32_f16 v[124:127], v[156:159], v[196:199], v[124:127]
	s_setprio 0
	s_add_i32 s28, s28, 2
	s_add_u32 s8, s8, 0x100
	s_addc_u32 s9, s9, 0
	s_add_u32 s26, s26, 0x100
	s_addc_u32 s27, s27, 0
	s_cmp_gt_u32 s28, 29
	s_cbranch_scc0 .LBB0_532
	s_and_b64 vcc, exec, s[50:51]
	s_cbranch_vccz .LBB0_535
	s_barrier

.LBB0_644:
	v_add_u32_e32 v240, 0x10000, v232
	s_mov_b32 s28, 2
	v_mov_b32_e32 v2, v132

.LBB0_649:
	s_or_b32 s38, s28, 1
	s_lshl_b64 s[42:43], s[38:39], 7
	s_sub_u32 s38, 0, s42
	s_subb_u32 s42, 0, s43
	s_add_u32 s38, s6, s38
	s_addc_u32 s43, s7, s42
	s_add_i32 s71, 0, 0x10000
	s_add_i32 s72, 0, 0x14000
	s_waitcnt lgkmcnt(0)
	ds_read_b128 v[132:135], v240
	ds_read_b128 v[136:139], v240 offset:1024
	ds_read_b128 v[140:143], v240 offset:2048
	ds_read_b128 v[144:147], v240 offset:3072
	ds_read_b128 v[148:151], v240 offset:16384
	ds_read_b128 v[152:155], v240 offset:17408
	ds_read_b128 v[156:159], v240 offset:18432
	ds_read_b128 v[160:163], v240 offset:19456
	s_add_u32 s42, s38, 0x160000
	s_mov_b32 m0, s64
	s_addc_u32 s43, s43, 0
	ds_read_b128 v[164:167], v231
	ds_read_b128 v[168:171], v231 offset:1024
	ds_read_b128 v[172:175], v231 offset:2048
	ds_read_b128 v[176:179], v231 offset:3072
	ds_read_b128 v[180:183], v231 offset:4096
	ds_read_b128 v[184:187], v231 offset:5120
	ds_read_b128 v[194:197], v231 offset:6144
	ds_read_b128 v[198:201], v231 offset:7168
	global_load_lds_dwordx4 v2, s[42:43]
	s_mov_b32 m0, s65
	v_mov_b32_e32 v189, v3
	global_load_lds_dwordx4 v188, s[42:43]
	s_waitcnt vmcnt(8)
	s_waitcnt lgkmcnt(0)
	s_barrier
	s_setprio 1
	s_waitcnt lgkmcnt(0)
	v_mfma_f32_16x16x32_bf16 v[4:7], v[132:135], v[164:167], v[4:7]
	v_mfma_f32_16x16x32_bf16 v[4:7], v[136:139], v[168:171], v[4:7]
	v_mfma_f32_16x16x32_bf16 v[8:11], v[144:147], v[168:171], v[8:11]
	v_mfma_f32_16x16x32_bf16 v[8:11], v[140:143], v[164:167], v[8:11]
	v_mfma_f32_16x16x32_bf16 v[16:19], v[140:143], v[172:175], v[16:19]
	v_mfma_f32_16x16x32_bf16 v[16:19], v[144:147], v[176:179], v[16:19]
	v_mfma_f32_16x16x32_bf16 v[12:15], v[136:139], v[176:179], v[12:15]
	v_mfma_f32_16x16x32_bf16 v[12:15], v[132:135], v[172:175], v[12:15]
	v_mfma_f32_16x16x32_bf16 v[20:23], v[132:135], v[180:183], v[20:23]
	v_mfma_f32_16x16x32_bf16 v[20:23], v[136:139], v[184:187], v[20:23]
	v_mfma_f32_16x16x32_bf16 v[24:27], v[144:147], v[184:187], v[24:27]
	v_mfma_f32_16x16x32_bf16 v[24:27], v[140:143], v[180:183], v[24:27]
	v_mfma_f32_16x16x32_bf16 v[32:35], v[140:143], v[194:197], v[32:35]
	v_mfma_f32_16x16x32_bf16 v[32:35], v[144:147], v[198:201], v[32:35]
	v_mfma_f32_16x16x32_bf16 v[28:31], v[136:139], v[198:201], v[28:31]
	v_mfma_f32_16x16x32_bf16 v[28:31], v[132:135], v[194:197], v[28:31]
	s_setprio 0
	s_setprio 1
	v_mfma_f32_16x16x32_bf16 v[36:39], v[148:151], v[164:167], v[36:39]
	v_mfma_f32_16x16x32_bf16 v[36:39], v[152:155], v[168:171], v[36:39]
	v_mfma_f32_16x16x32_bf16 v[40:43], v[160:163], v[168:171], v[40:43]
	v_mfma_f32_16x16x32_bf16 v[40:43], v[156:159], v[164:167], v[40:43]
	v_mfma_f32_16x16x32_bf16 v[48:51], v[156:159], v[172:175], v[48:51]
	v_mfma_f32_16x16x32_bf16 v[48:51], v[160:163], v[176:179], v[48:51]
	v_mfma_f32_16x16x32_bf16 v[44:47], v[152:155], v[176:179], v[44:47]
	v_mfma_f32_16x16x32_bf16 v[44:47], v[148:151], v[172:175], v[44:47]
	v_mfma_f32_16x16x32_bf16 v[52:55], v[148:151], v[180:183], v[52:55]
	v_mfma_f32_16x16x32_bf16 v[52:55], v[152:155], v[184:187], v[52:55]
	v_mfma_f32_16x16x32_bf16 v[56:59], v[160:163], v[184:187], v[56:59]
	v_mfma_f32_16x16x32_bf16 v[56:59], v[156:159], v[180:183], v[56:59]
	v_mfma_f32_16x16x32_bf16 v[64:67], v[156:159], v[194:197], v[64:67]
	v_mfma_f32_16x16x32_bf16 v[64:67], v[160:163], v[198:201], v[64:67]
	s_setprio 2
	s_barrier
	v_mfma_f32_16x16x32_bf16 v[60:63], v[152:155], v[198:201], v[60:63]
	v_mfma_f32_16x16x32_bf16 v[60:63], v[148:151], v[194:197], v[60:63]
	s_setprio 0
	s_add_i32 s38, s71, s54
	s_mov_b32 m0, s38
	ds_read_b128 v[164:167], v231 offset:16384
	ds_read_b128 v[168:171], v231 offset:17408
	ds_read_b128 v[172:175], v231 offset:18432
	ds_read_b128 v[176:179], v231 offset:19456
	ds_read_b128 v[180:183], v231 offset:20480
	ds_read_b128 v[184:187], v231 offset:21504
	ds_read_b128 v[194:197], v231 offset:22528
	ds_read_b128 v[198:201], v231 offset:23552
	global_load_lds_dwordx4 v192, s[16:17]
	s_add_i32 m0, s38, 0x2000
	s_add_u32 s42, s16, 0x160000
	s_addc_u32 s43, s17, 0
	s_add_i32 s38, s72, s54
	global_load_lds_dwordx4 v190, s[16:17]
	s_mov_b32 m0, s38
	v_mov_b32_e32 v193, v3
	global_load_lds_dwordx4 v192, s[42:43]
	s_add_i32 m0, s38, 0x2000
	v_mov_b32_e32 v191, v3
	global_load_lds_dwordx4 v190, s[42:43]
	s_mov_b32 m0, s55
	v_lshl_add_u64 v[202:203], s[16:17], 0, v[192:193]
	global_load_lds_dwordx4 v2, s[26:27]
	s_mov_b32 m0, s56
	v_lshl_add_u64 v[204:205], s[16:17], 0, v[190:191]
	global_load_lds_dwordx4 v188, s[26:27]
	s_waitcnt vmcnt(8)
	s_waitcnt lgkmcnt(0)
	v_lshl_add_u64 v[206:207], s[26:27], 0, v[2:3]
	v_lshl_add_u64 v[208:209], s[26:27], 0, v[188:189]
	s_barrier
	s_setprio 1
	s_waitcnt lgkmcnt(0)
	v_mfma_f32_16x16x32_bf16 v[68:71], v[132:135], v[164:167], v[68:71]
	v_mfma_f32_16x16x32_bf16 v[68:71], v[136:139], v[168:171], v[68:71]
	v_mfma_f32_16x16x32_bf16 v[72:75], v[144:147], v[168:171], v[72:75]
	v_mfma_f32_16x16x32_bf16 v[72:75], v[140:143], v[164:167], v[72:75]
	v_mfma_f32_16x16x32_bf16 v[80:83], v[140:143], v[172:175], v[80:83]
	v_mfma_f32_16x16x32_bf16 v[80:83], v[144:147], v[176:179], v[80:83]
	v_mfma_f32_16x16x32_bf16 v[76:79], v[136:139], v[176:179], v[76:79]
	v_mfma_f32_16x16x32_bf16 v[76:79], v[132:135], v[172:175], v[76:79]
	v_mfma_f32_16x16x32_bf16 v[84:87], v[132:135], v[180:183], v[84:87]
	v_mfma_f32_16x16x32_bf16 v[84:87], v[136:139], v[184:187], v[84:87]
	v_mfma_f32_16x16x32_bf16 v[88:91], v[144:147], v[184:187], v[88:91]
	v_mfma_f32_16x16x32_bf16 v[88:91], v[140:143], v[180:183], v[88:91]
	v_mfma_f32_16x16x32_bf16 v[96:99], v[140:143], v[194:197], v[96:99]
	v_mfma_f32_16x16x32_bf16 v[96:99], v[144:147], v[198:201], v[96:99]
	v_mfma_f32_16x16x32_bf16 v[92:95], v[136:139], v[198:201], v[92:95]
	v_mfma_f32_16x16x32_bf16 v[92:95], v[132:135], v[194:197], v[92:95]
	s_setprio 0
	s_setprio 1
	v_mfma_f32_16x16x32_bf16 v[100:103], v[148:151], v[164:167], v[100:103]
	v_mfma_f32_16x16x32_bf16 v[100:103], v[152:155], v[168:171], v[100:103]
	v_mfma_f32_16x16x32_bf16 v[104:107], v[160:163], v[168:171], v[104:107]
	v_mfma_f32_16x16x32_bf16 v[104:107], v[156:159], v[164:167], v[104:107]
	v_mfma_f32_16x16x32_bf16 v[112:115], v[156:159], v[172:175], v[112:115]
	v_mfma_f32_16x16x32_bf16 v[112:115], v[160:163], v[176:179], v[112:115]
	v_mfma_f32_16x16x32_bf16 v[108:111], v[152:155], v[176:179], v[108:111]
	v_mfma_f32_16x16x32_bf16 v[108:111], v[148:151], v[172:175], v[108:111]
	v_mfma_f32_16x16x32_bf16 v[116:119], v[148:151], v[180:183], v[116:119]
	v_mfma_f32_16x16x32_bf16 v[116:119], v[152:155], v[184:187], v[116:119]
	v_mfma_f32_16x16x32_bf16 v[120:123], v[160:163], v[184:187], v[120:123]
	v_mfma_f32_16x16x32_bf16 v[120:123], v[156:159], v[180:183], v[120:123]
	v_mfma_f32_16x16x32_bf16 v[128:131], v[156:159], v[194:197], v[128:131]
	v_mfma_f32_16x16x32_bf16 v[128:131], v[160:163], v[198:201], v[128:131]
	s_setprio 2
	s_barrier
	v_mfma_f32_16x16x32_bf16 v[124:127], v[152:155], v[198:201], v[124:127]
	v_mfma_f32_16x16x32_bf16 v[124:127], v[148:151], v[194:197], v[124:127]
	s_setprio 0
	s_add_i32 s38, 0, 0x18000
	s_add_i32 s42, 0, 0x1c000
	ds_read_b128 v[132:135], v240 offset:32768
	ds_read_b128 v[136:139], v240 offset:33792
	ds_read_b128 v[140:143], v240 offset:34816
	ds_read_b128 v[144:147], v240 offset:35840
	ds_read_b128 v[148:151], v240 offset:49152
	ds_read_b128 v[152:155], v240 offset:50176
	ds_read_b128 v[156:159], v240 offset:51200
	ds_read_b128 v[160:163], v240 offset:52224
	s_add_u32 s26, s26, 0x160000
	s_addc_u32 s27, s27, 0
	s_mov_b32 m0, s57
	ds_read_b128 v[164:167], v231 offset:32768
	ds_read_b128 v[168:171], v231 offset:33792
	ds_read_b128 v[172:175], v231 offset:34816
	ds_read_b128 v[176:179], v231 offset:35840
	ds_read_b128 v[180:183], v231 offset:36864
	ds_read_b128 v[184:187], v231 offset:37888
	ds_read_b128 v[194:197], v231 offset:38912
	ds_read_b128 v[198:201], v231 offset:39936
	global_load_lds_dwordx4 v2, s[26:27]
	s_mov_b32 m0, s58
	s_nop 0
	global_load_lds_dwordx4 v188, s[26:27]
	s_waitcnt vmcnt(8)
	s_waitcnt lgkmcnt(0)
	s_barrier
	s_setprio 1
	s_waitcnt lgkmcnt(0)
	v_mfma_f32_16x16x32_bf16 v[4:7], v[132:135], v[164:167], v[4:7]
	v_mfma_f32_16x16x32_bf16 v[4:7], v[136:139], v[168:171], v[4:7]
	v_mfma_f32_16x16x32_bf16 v[8:11], v[144:147], v[168:171], v[8:11]
	v_mfma_f32_16x16x32_bf16 v[8:11], v[140:143], v[164:167], v[8:11]
	v_mfma_f32_16x16x32_bf16 v[16:19], v[140:143], v[172:175], v[16:19]
	v_mfma_f32_16x16x32_bf16 v[16:19], v[144:147], v[176:179], v[16:19]
	v_mfma_f32_16x16x32_bf16 v[12:15], v[136:139], v[176:179], v[12:15]
	v_mfma_f32_16x16x32_bf16 v[12:15], v[132:135], v[172:175], v[12:15]
	v_mfma_f32_16x16x32_bf16 v[20:23], v[132:135], v[180:183], v[20:23]
	v_mfma_f32_16x16x32_bf16 v[20:23], v[136:139], v[184:187], v[20:23]
	v_mfma_f32_16x16x32_bf16 v[24:27], v[144:147], v[184:187], v[24:27]
	v_mfma_f32_16x16x32_bf16 v[24:27], v[140:143], v[180:183], v[24:27]
	v_mfma_f32_16x16x32_bf16 v[32:35], v[140:143], v[194:197], v[32:35]
	v_mfma_f32_16x16x32_bf16 v[32:35], v[144:147], v[198:201], v[32:35]
	v_mfma_f32_16x16x32_bf16 v[28:31], v[136:139], v[198:201], v[28:31]
	v_mfma_f32_16x16x32_bf16 v[28:31], v[132:135], v[194:197], v[28:31]
	s_setprio 0
	s_setprio 1
	v_mfma_f32_16x16x32_bf16 v[36:39], v[148:151], v[164:167], v[36:39]
	v_mfma_f32_16x16x32_bf16 v[36:39], v[152:155], v[168:171], v[36:39]
	v_mfma_f32_16x16x32_bf16 v[40:43], v[160:163], v[168:171], v[40:43]
	v_mfma_f32_16x16x32_bf16 v[40:43], v[156:159], v[164:167], v[40:43]
	v_mfma_f32_16x16x32_bf16 v[48:51], v[156:159], v[172:175], v[48:51]
	v_mfma_f32_16x16x32_bf16 v[48:51], v[160:163], v[176:179], v[48:51]
	v_mfma_f32_16x16x32_bf16 v[44:47], v[152:155], v[176:179], v[44:47]
	v_mfma_f32_16x16x32_bf16 v[44:47], v[148:151], v[172:175], v[44:47]
	v_mfma_f32_16x16x32_bf16 v[52:55], v[148:151], v[180:183], v[52:55]
	v_mfma_f32_16x16x32_bf16 v[52:55], v[152:155], v[184:187], v[52:55]
	v_mfma_f32_16x16x32_bf16 v[56:59], v[160:163], v[184:187], v[56:59]
	v_mfma_f32_16x16x32_bf16 v[56:59], v[156:159], v[180:183], v[56:59]
	v_mfma_f32_16x16x32_bf16 v[64:67], v[156:159], v[194:197], v[64:67]
	v_mfma_f32_16x16x32_bf16 v[64:67], v[160:163], v[198:201], v[64:67]
	s_setprio 2
	s_barrier
	v_mfma_f32_16x16x32_bf16 v[60:63], v[152:155], v[198:201], v[60:63]
	v_mfma_f32_16x16x32_bf16 v[60:63], v[148:151], v[194:197], v[60:63]
	s_setprio 0
	s_add_i32 s26, s38, s54
	v_lshl_add_u64 v[202:203], v[202:203], 0, s[4:5]
	s_mov_b32 m0, s26
	ds_read_b128 v[164:167], v231 offset:49152
	ds_read_b128 v[168:171], v231 offset:50176
	ds_read_b128 v[172:175], v231 offset:51200
	ds_read_b128 v[176:179], v231 offset:52224
	ds_read_b128 v[180:183], v231 offset:53248
	ds_read_b128 v[184:187], v231 offset:54272
	ds_read_b128 v[194:197], v231 offset:55296
	ds_read_b128 v[198:201], v231 offset:56320
	global_load_lds_dwordx4 v[202:203], off
	s_add_i32 m0, s26, 0x2000
	s_add_u32 s16, s16, 0x15ff80
	v_lshl_add_u64 v[202:203], v[204:205], 0, s[4:5]
	s_addc_u32 s17, s17, 0
	s_add_i32 s26, s42, s54
	global_load_lds_dwordx4 v[202:203], off
	s_mov_b32 m0, s26
	v_lshl_add_u64 v[202:203], v[206:207], 0, s[4:5]
	global_load_lds_dwordx4 v192, s[16:17]
	s_add_i32 m0, s26, 0x2000
	s_nop 0
	global_load_lds_dwordx4 v190, s[16:17]
	s_mov_b32 m0, s62
	s_nop 0
	global_load_lds_dwordx4 v[202:203], off
	v_lshl_add_u64 v[202:203], v[208:209], 0, s[4:5]
	s_mov_b32 m0, s63
	s_nop 0
	global_load_lds_dwordx4 v[202:203], off
	s_waitcnt vmcnt(8)
	s_waitcnt lgkmcnt(0)
	s_barrier
	s_setprio 1
	s_waitcnt lgkmcnt(0)
	v_mfma_f32_16x16x32_bf16 v[68:71], v[132:135], v[164:167], v[68:71]
	v_mfma_f32_16x16x32_bf16 v[68:71], v[136:139], v[168:171], v[68:71]
	v_mfma_f32_16x16x32_bf16 v[72:75], v[144:147], v[168:171], v[72:75]
	v_mfma_f32_16x16x32_bf16 v[72:75], v[140:143], v[164:167], v[72:75]
	v_mfma_f32_16x16x32_bf16 v[80:83], v[140:143], v[172:175], v[80:83]
	v_mfma_f32_16x16x32_bf16 v[80:83], v[144:147], v[176:179], v[80:83]
	v_mfma_f32_16x16x32_bf16 v[76:79], v[136:139], v[176:179], v[76:79]
	v_mfma_f32_16x16x32_bf16 v[76:79], v[132:135], v[172:175], v[76:79]
	v_mfma_f32_16x16x32_bf16 v[84:87], v[132:135], v[180:183], v[84:87]
	v_mfma_f32_16x16x32_bf16 v[84:87], v[136:139], v[184:187], v[84:87]
	v_mfma_f32_16x16x32_bf16 v[88:91], v[144:147], v[184:187], v[88:91]
	v_mfma_f32_16x16x32_bf16 v[88:91], v[140:143], v[180:183], v[88:91]
	v_mfma_f32_16x16x32_bf16 v[96:99], v[140:143], v[194:197], v[96:99]
	v_mfma_f32_16x16x32_bf16 v[96:99], v[144:147], v[198:201], v[96:99]
	v_mfma_f32_16x16x32_bf16 v[92:95], v[136:139], v[198:201], v[92:95]
	v_mfma_f32_16x16x32_bf16 v[92:95], v[132:135], v[194:197], v[92:95]
	s_setprio 0
	s_setprio 1
	v_mfma_f32_16x16x32_bf16 v[100:103], v[148:151], v[164:167], v[100:103]
	v_mfma_f32_16x16x32_bf16 v[100:103], v[152:155], v[168:171], v[100:103]
	v_mfma_f32_16x16x32_bf16 v[104:107], v[160:163], v[168:171], v[104:107]
	v_mfma_f32_16x16x32_bf16 v[104:107], v[156:159], v[164:167], v[104:107]
	v_mfma_f32_16x16x32_bf16 v[112:115], v[156:159], v[172:175], v[112:115]
	v_mfma_f32_16x16x32_bf16 v[112:115], v[160:163], v[176:179], v[112:115]
	v_mfma_f32_16x16x32_bf16 v[108:111], v[152:155], v[176:179], v[108:111]
	v_mfma_f32_16x16x32_bf16 v[108:111], v[148:151], v[172:175], v[108:111]
	v_mfma_f32_16x16x32_bf16 v[116:119], v[148:151], v[180:183], v[116:119]
	v_mfma_f32_16x16x32_bf16 v[116:119], v[152:155], v[184:187], v[116:119]
	v_mfma_f32_16x16x32_bf16 v[120:123], v[160:163], v[184:187], v[120:123]
	v_mfma_f32_16x16x32_bf16 v[120:123], v[156:159], v[180:183], v[120:123]
	v_mfma_f32_16x16x32_bf16 v[128:131], v[156:159], v[194:197], v[128:131]
	v_mfma_f32_16x16x32_bf16 v[128:131], v[160:163], v[198:201], v[128:131]
	s_setprio 2
	s_barrier
	v_mfma_f32_16x16x32_bf16 v[124:127], v[152:155], v[198:201], v[124:127]
	v_mfma_f32_16x16x32_bf16 v[124:127], v[148:151], v[194:197], v[124:127]
	s_setprio 0
	s_cmpk_gt_u32 s28, 0x55
	s_cbranch_scc1 .LBB0_651
	s_mov_b32 s28, s29
	s_branch .LBB0_645
